# P7: pair super-chunk j with j^47 so waves owning a sample unit get shorter Horner chains (on top of pipelined Horner + hoisted unit loads + P1 plain f32 stores)
# baseline (speedup 1.0000x reference)
; template <int PASS> __device__ __forceinline__ void ssm_unit(int unit, int lane, LAS unsigned char* wl, const bf16* X2, const float* slots, float* RSTD, const float* gmix, const float* AB, const float* A128, const bf16* BB, const bf16* CC, ...
;     ...
;     { const f32x2 abA = *(const f32x2*)(AB + (size_t)(g * 64 + n) * 2), abB = *(const f32x2*)(AB + (size_t)(g * 64 + n + 32) * 2);
;       aA = {abA.x, abA.y}; aB = {abB.x, abB.y};
;       cpx t = cmul(aA, aA); t = cmul(t, t); aA8 = cmul(t, t); t = cmul(aB, aB); t = cmul(t, t); aB8 = cmul(t, t); }
;     bf16x8 bbf[4];
; #pragma unroll
;     for (int b = 0; b < 4; ++b) bbf[b] = ld8_bf16(BB + ((size_t)g * 128 + b * 32 + n) * 16 + 8 * hi);
;     cpx SA = {0.f, 0.f}, SB = {0.f, 0.f};
;     if (PASS == 2) {
;         if (smp) { const size_t o = (size_t)(sc - 128) * 4096 + g * 64 + n; SA = {h0r[o], h0i[o]}; SB = {h0r[o + 32], h0i[o + 32]}; }
;         else {
;             const f32x2 pA = *(const f32x2*)(A128 + (size_t)(g * 64 + n) * 2), pB = *(const f32x2*)(A128 + (size_t)(g * 64 + n + 32) * 2);
;             const cpx qA = {pA.x, pA.y}, qB = {pB.x, pB.y};
;             const int c0 = sc & ~63, nc = sc & 63;
;             const float* ep = E + ((size_t)c0 * 4096 + g * 64 + n) * 2;
; #pragma unroll 4
;             for (int c = 0; c < nc; ++c) { const f32x2 eA = *(const f32x2*)(ep + (size_t)c * 8192), eB = *(const f32x2*)(ep + (size_t)c * 8192 + 64);
;                 SA = cfma(qA, SA, (cpx){eA.x, eA.y}); SB = cfma(qB, SB, (cpx){eB.x, eB.y}); }
;         }
;     }
;     LAS unsigned char* Sl = wl;
;     LAS float* Ul = (LAS float*)(wl + 128 * SSM_IROW);
;     bf16x8 ccf[4]; f32x4 dv = {0.f, 0.f, 0.f, 0.f};
;     const int c16 = lane & 15, kq = lane >> 4;
;     if (PASS == 2) {
; #pragma unroll
; __global__ void __launch_bounds__(512, 2) mk_fwd(Params p) {
;     ...
;         for (int u0 = gw; u0 < 144 * 64; u0 += NGW) {
;             int u = u0;
;             if (u0 < 128 * 64) { const int k = u0 >> 11, s0 = (u0 >> 6) & 31, j = (k & 1) ? 63 - s0 : s0; u = (((k >> 1) * 64 + j) << 6) | (u0 & 63); }
;             ssm_unit<2>(u, lane, wl, WSB(bf16, WS_RA), WSB(float, WS_SL2), WSB(float, WS_RSTD), p.in[6] + D, WSB(float, WS_AB), WSB(float, WS_A128), WSB(bf16, WS_BB), WSB(bf16, WS_CC), p.in[20], WSB(float, WS_E), p.in[4], p.in[5], WSB(bf16, WS_RD), OUTP(O_RP), OUTP(O_IP), OUTP(O_RS), OUTP(O_IS));
.LBB0_720:
	s_and_b32 s4, s74, 0x7c0
	s_and_b32 s5, s74, 0x800
	s_xor_b32 s14, s4, 0xbc0
	s_cmp_eq_u32 s5, 0
	s_cselect_b32 s4, s4, s14
	s_and_b32 s5, s74, 0xfffff03f
	s_or_b32 s4, s4, s5
	s_cmpk_lt_i32 s74, 0x2000
	s_cselect_b32 s72, s4, s74
	s_and_b32 s4, s72, 63
	s_ashr_i32 s75, s72, 6
	s_cmpk_gt_i32 s75, 0x7f
	s_cselect_b64 s[46:47], -1, 0
	s_cmpk_lt_i32 s75, 0x80
	s_cselect_b64 s[44:45], -1, 0
	s_lshl_b32 s34, s4, 6
	v_or_b32_e32 v1, s34, v162
	v_lshlrev_b32_e32 v0, 1, v1
	v_lshlrev_b32_e32 v2, 3, v1
	v_or_b32_e32 v1, 64, v0
	s_lshl_b32 s5, s4, 11
	v_lshlrev_b32_e32 v1, 2, v1
	global_load_dwordx2 v[128:129], v2, s[64:65]
	global_load_dwordx2 v[130:131], v1, s[64:65]
	v_or_b32_e32 v2, s5, v153
	v_lshlrev_b32_e32 v112, 1, v2
	v_lshl_add_u64 v[2:3], v[114:115], 0, v[112:113]
	global_load_dwordx4 v[64:67], v[2:3], off
	global_load_dwordx4 v[68:71], v[2:3], off offset:1024
	global_load_dwordx4 v[72:75], v[2:3], off offset:2048
	global_load_dwordx4 v[76:79], v[2:3], off offset:3072
	s_and_b32 s98, s72, 0xffffffc0
	s_addk_i32 s98, 0x2000
	s_lshl_b32 s99, s75, 7
	s_and_b64 s[100:101], s[46:47], exec
	s_cselect_b32 s98, s98, s99
	v_or_b32_e32 v207, s5, v159
	v_lshlrev_b32_e32 v208, 1, v207
	v_mov_b32_e32 v209, 0
	v_lshl_add_u64 v[210:211], v[116:117], 0, v[208:209]
	global_load_dwordx4 v[80:83], v[210:211], off
	global_load_dwordx4 v[84:87], v[210:211], off offset:64
	global_load_dwordx4 v[88:91], v[210:211], off offset:128
	global_load_dwordx4 v[92:95], v[210:211], off offset:192
	v_lshl_add_u64 v[210:211], v[118:119], 0, s[34:35]
	global_load_dwordx4 v[96:99], v[210:211], off
	v_lshl_add_u64 v[210:211], v[120:121], 0, s[34:35]
	global_load_dwordx4 v[100:103], v[210:211], off offset:16
	global_load_dwordx4 v[104:107], v[210:211], off
	v_or_b32_e32 v214, s98, v157
	v_ashrrev_i32_e32 v215, 31, v214
	v_lshlrev_b64 v[216:217], 11, v[214:215]
	v_lshl_add_u64 v[216:217], s[20:21], 0, v[216:217]
	s_lshl_b32 s100, s4, 5
	s_mov_b32 s101, s35
	v_lshl_add_u64 v[216:217], v[216:217], 0, s[100:101]
	v_mov_b32_e32 v218, v126
	v_mov_b32_e32 v219, 0
	v_lshl_add_u64 v[216:217], v[216:217], 0, v[218:219]
	v_lshl_add_u64 v[220:221], v[214:215], 2, s[22:23]
	global_load_dwordx4 v[202:205], v[216:217], off
	s_nop 0
	global_load_dword v206, v[220:221], off
	s_mov_b64 s[68:69], -1
	s_and_b64 vcc, exec, s[44:45]
	s_cbranch_vccz .LBB0_731
	s_bfe_u32 s70, s72, 0x60006
	s_cmp_eq_u32 s70, 0
	s_cbranch_scc1 .LBB0_726
	v_lshlrev_b32_e32 v0, 2, v0
	global_load_dwordx2 v[4:5], v1, s[66:67]
	global_load_dwordx2 v[8:9], v0, s[66:67]
	s_and_b32 s68, s75, 0xffffffc0
	s_ashr_i32 s69, s68, 31
	s_lshl_b64 s[68:69], s[68:69], 12
	s_cmp_lt_u32 s70, 4
	s_waitcnt vmcnt(1)
	v_xor_b32_e32 v0, 0x80000000, v5
	v_mov_b32_e32 v2, v4
	v_mov_b32_e32 v3, v4
	v_mov_b32_e32 v1, v5
	s_waitcnt vmcnt(0)
	v_xor_b32_e32 v4, 0x80000000, v9
	v_mov_b32_e32 v6, v8
	v_mov_b32_e32 v7, v8
	v_mov_b32_e32 v5, v9
	s_cbranch_scc1 .LBB0_727
	s_and_b32 s70, s75, 60
	s_add_u32 s76, s34, s68
	s_addc_u32 s77, 0, s69
	v_lshl_add_u64 v[8:9], s[76:77], 0, v[162:163]
	v_mov_b32_e32 v132, 0
	v_lshl_add_u64 v[8:9], v[8:9], 3, s[36:37]
	s_mov_b32 s71, 0
	v_mov_b32_e32 v133, v132
	v_mov_b32_e32 v164, v132
	v_mov_b32_e32 v165, v132
